# onorm row loop software-pipelined: next row's loads issued one iteration early into shadow registers, counted vmcnt(4) wait, global_ instead of flat_ memory ops
# baseline (speedup 1.0000x reference)
; DI void onorm_pass(const Params& p, const float* __restrict__ ggrp, int bid, int nb, const int tid) {
;     const int wave = __builtin_amdgcn_readfirstlane(tid >> 6), lane = tid & 63;
;     const float* Y = (const float*)(p.ws + B_Y);
;     bf16_t* XN = (bf16_t*)(p.ws + B_XN);
;     for (int row = bid * NWAVE + wave; row < MT; row += nb * NWAVE) {
;         float4 y[4]; float ss[4];
; #pragma unroll
;         for (int i = 0; i < 4; ++i) {
;             y[i] = *(const float4*)(Y + (size_t)row * DM + i * 256 + lane * 4);
;             ss[i] = wave_sum(y[i].x * y[i].x + y[i].y * y[i].y + y[i].z * y[i].z + y[i].w * y[i].w);
;         }
.LBB0_272:
	s_and_b64 vcc, exec, s[0:1]
	s_cbranch_vccz .LBB0_276
	v_readfirstlane_b32 s0, v227
	v_readlane_b32 s2, v231, 0
	s_ashr_i32 s0, s0, 6
	s_lshl_b32 s1, s2, 3
	s_add_i32 s2, s0, s1
	s_cmpk_gt_i32 s2, 0x40ff
	v_readlane_b32 s3, v231, 1
	s_cbranch_scc1 .LBB0_276
	v_readlane_b32 s3, v231, 4
	s_lshl_b32 s10, s3, 10
	s_ashr_i32 s11, s10, 31
	v_readlane_b32 s48, v240, 29
	s_lshl_b64 s[10:11], s[10:11], 2
	v_readlane_b32 s62, v240, 43
	v_readlane_b32 s63, v240, 44
	s_add_u32 s10, s62, s10
	v_lshlrev_b32_e32 v0, 4, v227
	s_addc_u32 s11, s63, s11
	v_and_b32_e32 v12, 0x3f0, v0
	global_load_dwordx4 v[0:3], v12, s[10:11]
	global_load_dwordx4 v[4:7], v12, s[10:11] offset:1024
	global_load_dwordx4 v[8:11], v12, s[10:11] offset:2048
	s_nop 0
	global_load_dwordx4 v[12:15], v12, s[10:11] offset:3072
	v_cmp_lt_i32_e32 vcc, v217, v216
	s_ashr_i32 s3, s0, 31
	s_ashr_i32 s10, s1, 31
	v_cndmask_b32_e32 v17, v214, v217, vcc
	v_cmp_lt_i32_e32 vcc, v218, v216
	s_add_u32 s0, s0, s1
	s_addc_u32 s1, s3, s10
	v_cndmask_b32_e32 v18, v214, v218, vcc
	v_cmp_lt_i32_e32 vcc, v219, v216
	v_lshlrev_b32_e32 v26, 2, v18
	s_lshl_b64 s[10:11], s[0:1], 12
	v_cndmask_b32_e32 v18, v214, v219, vcc
	v_cmp_lt_i32_e32 vcc, v220, v216
	v_lshlrev_b32_e32 v27, 2, v18
	v_and_b32_e32 v24, 63, v227
	v_cndmask_b32_e32 v18, v214, v220, vcc
	v_lshlrev_b32_e32 v28, 2, v18
	v_lshl_or_b32 v18, v24, 4, s10
	v_mov_b32_e32 v19, s11
	s_lshl_b64 s[0:1], s[0:1], 11
	s_mov_b32 s10, 0x3b800000
	v_readlane_b32 s38, v238, 42
	v_lshlrev_b32_e32 v17, 2, v17
	v_lshl_or_b32 v24, v24, 3, s0
	v_mov_b32_e32 v25, s1
	s_mov_b32 s11, 0x3b000000
	v_readlane_b32 s39, v238, 43
	v_readlane_b32 s49, v240, 30
	v_readlane_b32 s50, v240, 31
	v_readlane_b32 s51, v240, 32
	v_readlane_b32 s52, v240, 33
	v_readlane_b32 s53, v240, 34
	v_readlane_b32 s54, v240, 35
	v_readlane_b32 s55, v240, 36
	v_readlane_b32 s56, v240, 37
	v_readlane_b32 s57, v240, 38
	v_readlane_b32 s58, v240, 39
	v_readlane_b32 s59, v240, 40
	v_readlane_b32 s60, v240, 41
	v_readlane_b32 s61, v240, 42
	v_lshl_add_u64 v[80:81], s[88:89], 0, v[18:19]
	v_add_co_u32_e32 v80, vcc, 0xac20000, v80
	s_nop 1
	v_addc_co_u32_e32 v81, vcc, 0, v81, vcc
	global_load_dwordx4 v[64:67], v[80:81], off offset:2048
	global_load_dwordx4 v[68:71], v[80:81], off
	global_load_dwordx4 v[72:75], v[80:81], off offset:1024
	global_load_dwordx4 v[76:79], v[80:81], off offset:3072
	v_lshl_add_u64 v[18:19], v[18:19], 0, s[30:31]
	s_waitcnt vmcnt(0) lgkmcnt(0)
	s_branch .Lon_body
.LBB0_275:
	s_waitcnt vmcnt(4)
.Lon_body:
	v_mov_b64_e32 v[30:31], v[64:65]
	v_mov_b64_e32 v[32:33], v[66:67]
	v_mov_b64_e32 v[34:35], v[68:69]
	v_mov_b64_e32 v[36:37], v[70:71]
	v_mov_b64_e32 v[38:39], v[72:73]
	v_mov_b64_e32 v[40:41], v[74:75]
	v_mov_b64_e32 v[42:43], v[76:77]
	v_mov_b64_e32 v[44:45], v[78:79]
	v_lshl_add_u64 v[82:83], s[88:89], 0, v[24:25]
	v_add_co_u32_e32 v46, vcc, 0x3240000, v82
	s_nop 1
	v_addc_co_u32_e32 v47, vcc, 0, v83, vcc
	s_add_i32 s2, s2, s94
	v_lshl_add_u64 v[24:25], v[24:25], 0, s[38:39]
	s_cmpk_gt_i32 s2, 0x40ff
	s_cbranch_scc1 .Lon_nopf
	v_lshl_add_u64 v[80:81], s[88:89], 0, v[18:19]
	v_add_co_u32_e32 v80, vcc, 0xac20000, v80
	s_nop 1
	v_addc_co_u32_e32 v81, vcc, 0, v81, vcc
	global_load_dwordx4 v[64:67], v[80:81], off offset:2048
	global_load_dwordx4 v[68:71], v[80:81], off
	global_load_dwordx4 v[72:75], v[80:81], off offset:1024
	global_load_dwordx4 v[76:79], v[80:81], off offset:3072
	v_lshl_add_u64 v[18:19], v[18:19], 0, s[30:31]
; DI unsigned pk2(float lo, float hi) { const f32x2 v = {lo, hi}; return __builtin_bit_cast(unsigned, __builtin_convertvector(v, bf2_t)); }
; DI void onorm_pass(const Params& p, const float* __restrict__ ggrp, int bid, int nb, const int tid) {
;     ...
;             ss[i] = wave_sum(y[i].x * y[i].x + y[i].y * y[i].y + y[i].z * y[i].z + y[i].w * y[i].w);
;         }
;         const float ra = rsqrtf(ss[0] * (1.0f / 256) + EPS), rb = rsqrtf((ss[1] + ss[2]) * (1.0f / 512) + EPS), rc = rsqrtf(ss[3] * (1.0f / 256) + EPS);
; #pragma unroll
;         for (int i = 0; i < 4; ++i) {
;             const float r = i == 0 ? ra : (i == 3 ? rc : rb);
;             const float4 g = *(const float4*)(ggrp + i * 256 + lane * 4);
;             u32x2 w; w.x = pk2(y[i].x * r * g.x, y[i].y * r * g.y); w.y = pk2(y[i].z * r * g.z, y[i].w * r * g.w);
;             *(u32x2*)(XN + (size_t)row * DM + i * 256 + lane * 4) = w;
;         }
;     }
.Lon_nopf:
	v_mul_f32_e32 v48, v31, v31
	v_mul_f32_e32 v52, v35, v35
	v_mul_f32_e32 v56, v39, v39
	v_mul_f32_e32 v60, v43, v43
	v_pk_fma_f32 v[48:49], v[30:31], v[30:31], v[48:49] op_sel_hi:[1,1,0]
	v_pk_fma_f32 v[52:53], v[34:35], v[34:35], v[52:53] op_sel_hi:[1,1,0]
	v_pk_fma_f32 v[56:57], v[38:39], v[38:39], v[56:57] op_sel_hi:[1,1,0]
	v_mul_f32_e32 v50, v33, v33
	v_mul_f32_e32 v54, v37, v37
	v_mul_f32_e32 v58, v41, v41
	v_pk_fma_f32 v[60:61], v[42:43], v[42:43], v[60:61] op_sel_hi:[1,1,0]
	v_pk_fma_f32 v[48:49], v[32:33], v[32:33], v[48:49]
	v_pk_fma_f32 v[52:53], v[36:37], v[36:37], v[52:53]
	v_pk_fma_f32 v[56:57], v[40:41], v[40:41], v[56:57]
	v_mul_f32_e32 v62, v45, v45
	v_pk_fma_f32 v[60:61], v[44:45], v[44:45], v[60:61]
	v_pk_add_f32 v[48:49], v[48:49], v[50:51] op_sel_hi:[1,0]
	v_pk_add_f32 v[50:51], v[52:53], v[54:55] op_sel_hi:[1,0]
	v_pk_add_f32 v[52:53], v[56:57], v[58:59] op_sel_hi:[1,0]
	v_pk_add_f32 v[54:55], v[60:61], v[62:63] op_sel_hi:[1,0]
	v_mov_b32_e32 v29, v48
	v_mov_b32_e32 v51, v50
	v_mov_b32_e32 v53, v52
	v_mov_b32_e32 v55, v54
	v_permlane32_swap_b32_e32 v48, v29
	v_permlane32_swap_b32_e32 v50, v51
	v_permlane32_swap_b32_e32 v52, v53
	v_permlane32_swap_b32_e32 v54, v55
	v_add_f32_e32 v49, v48, v29
	v_add_f32_e32 v29, v50, v51
	v_add_f32_e32 v48, v52, v53
	v_add_f32_e32 v52, v54, v55
	v_mov_b32_e32 v51, v49
	v_mov_b32_e32 v53, v29
	v_mov_b32_e32 v50, v48
	v_mov_b32_e32 v54, v52
	v_permlane16_swap_b32_e32 v49, v51
	v_permlane16_swap_b32_e32 v29, v53
	v_permlane16_swap_b32_e32 v48, v50
	v_permlane16_swap_b32_e32 v52, v54
	v_add_f32_e32 v29, v29, v53
	v_pk_add_f32 v[48:49], v[48:49], v[50:51]
	v_add_f32_e32 v52, v52, v54
	ds_bpermute_b32 v53, v17, v29
	ds_bpermute_b32 v51, v17, v49
	ds_bpermute_b32 v50, v17, v48
	ds_bpermute_b32 v54, v17, v52
	s_waitcnt lgkmcnt(3)
	v_add_f32_e32 v29, v29, v53
	ds_bpermute_b32 v53, v26, v29
	s_waitcnt lgkmcnt(2)
	v_pk_add_f32 v[48:49], v[48:49], v[50:51]
	s_waitcnt lgkmcnt(1)
	v_add_f32_e32 v52, v52, v54
	ds_bpermute_b32 v51, v26, v49
	ds_bpermute_b32 v50, v26, v48
	ds_bpermute_b32 v54, v26, v52
	s_waitcnt lgkmcnt(3)
	v_add_f32_e32 v29, v29, v53
	ds_bpermute_b32 v53, v27, v29
	s_waitcnt lgkmcnt(2)
	v_pk_add_f32 v[48:49], v[48:49], v[50:51]
	s_waitcnt lgkmcnt(1)
	v_add_f32_e32 v52, v52, v54
	ds_bpermute_b32 v51, v27, v49
	ds_bpermute_b32 v50, v27, v48
	ds_bpermute_b32 v54, v27, v52
	s_waitcnt lgkmcnt(3)
	v_add_f32_e32 v29, v29, v53
	s_waitcnt lgkmcnt(1)
	v_pk_add_f32 v[48:49], v[48:49], v[50:51]
	s_waitcnt lgkmcnt(0)
	v_add_f32_e32 v50, v52, v54
	ds_bpermute_b32 v51, v28, v29
	ds_bpermute_b32 v53, v28, v49
	ds_bpermute_b32 v52, v28, v48
	ds_bpermute_b32 v54, v28, v50
	s_waitcnt lgkmcnt(3)
	v_add_f32_e32 v29, v29, v51
	v_fmamk_f32 v29, v29, 0x3b800000, v192
	s_waitcnt lgkmcnt(1)
	v_pk_add_f32 v[48:49], v[48:49], v[52:53]
	v_mul_f32_e32 v52, 0x4b800000, v29
	v_mov_b32_e32 v51, v48
	v_mov_b32_e32 v55, v49
	s_waitcnt lgkmcnt(0)
	v_pk_add_f32 v[48:49], v[50:51], v[54:55]
	v_cmp_gt_f32_e32 vcc, s86, v29
	v_pk_fma_f32 v[48:49], v[48:49], s[10:11], v[192:193] op_sel_hi:[1,1,0]
	s_nop 0
	v_cndmask_b32_e32 v29, v29, v52, vcc
	v_rsq_f32_e32 v29, v29
	v_mul_f32_e32 v50, 0x4b800000, v49
	v_cmp_gt_f32_e64 s[36:37], s86, v49
	v_mul_f32_e32 v51, 0x4b800000, v48
	v_cmp_gt_f32_e64 s[0:1], s86, v48
	v_cndmask_b32_e64 v49, v49, v50, s[36:37]
	v_rsq_f32_e32 v49, v49
	v_cndmask_b32_e64 v48, v48, v51, s[0:1]
	v_rsq_f32_e32 v50, v48
	v_mul_f32_e32 v48, 0x45800000, v29
	v_cndmask_b32_e32 v48, v29, v48, vcc
	v_pk_mul_f32 v[34:35], v[34:35], v[48:49] op_sel_hi:[1,0]
	v_pk_mul_f32 v[36:37], v[36:37], v[48:49] op_sel_hi:[1,0]
	v_mul_f32_e32 v29, 0x45800000, v49
	v_mul_f32_e32 v51, 0x45800000, v50
	v_pk_mul_f32 v[34:35], v[0:1], v[34:35]
	v_pk_mul_f32 v[36:37], v[2:3], v[36:37]
	v_cndmask_b32_e64 v48, v49, v29, s[36:37]
	v_cndmask_b32_e64 v50, v50, v51, s[0:1]
	v_cvt_pk_bf16_f32 v34, v34, v35
	v_cvt_pk_bf16_f32 v35, v36, v37
	v_pk_mul_f32 v[36:37], v[38:39], v[48:49] op_sel_hi:[1,0]
	v_pk_mul_f32 v[38:39], v[40:41], v[48:49] op_sel_hi:[1,0]
	v_pk_mul_f32 v[30:31], v[30:31], v[48:49] op_sel_hi:[1,0]
	v_pk_mul_f32 v[32:33], v[32:33], v[48:49] op_sel_hi:[1,0]
	v_pk_mul_f32 v[40:41], v[42:43], v[50:51] op_sel_hi:[1,0]
	v_pk_mul_f32 v[42:43], v[44:45], v[50:51] op_sel_hi:[1,0]
	v_pk_mul_f32 v[36:37], v[4:5], v[36:37]
	v_pk_mul_f32 v[38:39], v[6:7], v[38:39]
	v_pk_mul_f32 v[30:31], v[8:9], v[30:31]
	v_pk_mul_f32 v[32:33], v[10:11], v[32:33]
	global_store_dwordx2 v[46:47], v[34:35], off
	v_pk_mul_f32 v[34:35], v[12:13], v[40:41]
	v_pk_mul_f32 v[40:41], v[14:15], v[42:43]
	v_cvt_pk_bf16_f32 v36, v36, v37
	v_cvt_pk_bf16_f32 v37, v38, v39
	v_cvt_pk_bf16_f32 v30, v30, v31
	v_cvt_pk_bf16_f32 v31, v32, v33
	v_cvt_pk_bf16_f32 v32, v34, v35
	v_cvt_pk_bf16_f32 v33, v40, v41
	global_store_dwordx2 v[46:47], v[36:37], off offset:512
	global_store_dwordx2 v[46:47], v[30:31], off offset:1024
	global_store_dwordx2 v[46:47], v[32:33], off offset:1536
	s_cmpk_gt_i32 s2, 0x40ff
	s_cbranch_scc0 .LBB0_275
